# batch the 8 serialized stream-state loads of sample-row tiles in the FFN up epilogue (one round trip per ai instead of four)
# speedup vs baseline: 1.0035x; 1.0001x over previous
; #define GAS __attribute__((address_space(1)))
; #define LAS __attribute__((address_space(3)))
; __device__ __forceinline__ unsigned pk_bf16(float lo, float hi) { f32x2_t v = {lo, hi}; bf16x2_t b = __builtin_convertvector(v, bf16x2_t); return __builtin_bit_cast(unsigned, b); }
;     __device__ __forceinline__ void operator()(EPI_ARGS) const {
;     ...
;             for (int q = 0; q < 4; ++q) {
;                 const int c2 = ch + 2 * q;
;                 const f32x2_t bg = {BG[q >> 1][2 * (q & 1)], BG[q >> 1][2 * (q & 1) + 1]}, bv = {BV[q >> 1][2 * (q & 1)], BV[q >> 1][2 * (q & 1) + 1]};
;                 const LAS float* xp = X + (pred * 2 + hsel) * 256 + cl + 2 * q;
;                 const f32x2_t xgv = *(const LAS f32x2_t*)xp, xvv = *(const LAS f32x2_t*)(xp + HALF);
;                 unsigned hg = use_x ? pk_bf16(xgv.x, xgv.y) : 0u, hv = use_x ? pk_bf16(xvv.x, xvv.y) : 0u;
;                 if (samp) { const float* sp = sfs + ((size_t)sb * 2 + hsel) * FF2 + c2; const f32x2_t sgv = *(const GAS f32x2_t*)sp, svv = *(const GAS f32x2_t*)(sp + FF); hg = pk_bf16(sgv.x, sgv.y); hv = pk_bf16(svv.x, svv.y); }
.LBB0_1409:
	s_add_i32 s10, s62, 0xffff0000
	s_ashr_i32 s10, s10, 6
	v_lshl_or_b32 v102, s10, 1, v97
	v_mov_b64_e32 v[64:65], s[26:27]
	s_movk_i32 s10, 0x5800
	v_mad_i64_i32 v[64:65], s[10:11], v102, s10, v[64:65]
	v_cndmask_b32_e64 v102, 0, 1, s[48:49]
	v_cmp_ne_u32_e64 s[10:11], 1, v102
	s_andn2_b64 vcc, exec, s[48:49]
	v_lshl_add_u64 v[64:65], v[142:143], 2, v[64:65]
	s_cbranch_vccnz .LBB0_1411
	s_waitcnt lgkmcnt(0)
	v_add_co_u32_e32 v66, vcc, 0x2000, v64
	s_nop 1
	v_addc_co_u32_e32 v67, vcc, 0, v65, vcc
	global_load_dwordx2 v[102:103], v[64:65], off
	global_load_dwordx2 v[230:231], v[64:65], off offset:8
	global_load_dwordx2 v[232:233], v[64:65], off offset:16
	global_load_dwordx2 v[234:235], v[64:65], off offset:24
	global_load_dwordx2 v[236:237], v[66:67], off offset:3080
	global_load_dwordx2 v[238:239], v[66:67], off offset:3088
	global_load_dwordx2 v[240:241], v[66:67], off offset:3096
	s_nop 0
	global_load_dwordx2 v[66:67], v[66:67], off offset:3072
	s_waitcnt vmcnt(7)
	v_cvt_pk_bf16_f32 v99, v102, v103
	s_waitcnt vmcnt(0)
	v_cvt_pk_bf16_f32 v66, v66, v67
	s_branch .LBB0_1412

; #define GAS __attribute__((address_space(1)))
; #define LAS __attribute__((address_space(3)))
; __device__ __forceinline__ unsigned pk_bf16(float lo, float hi) { f32x2_t v = {lo, hi}; bf16x2_t b = __builtin_convertvector(v, bf16x2_t); return __builtin_bit_cast(unsigned, b); }
;     __device__ __forceinline__ void operator()(EPI_ARGS) const {
;     ...
;             for (int q = 0; q < 4; ++q) {
;                 const int c2 = ch + 2 * q;
;                 const f32x2_t bg = {BG[q >> 1][2 * (q & 1)], BG[q >> 1][2 * (q & 1) + 1]}, bv = {BV[q >> 1][2 * (q & 1)], BV[q >> 1][2 * (q & 1) + 1]};
;                 const LAS float* xp = X + (pred * 2 + hsel) * 256 + cl + 2 * q;
;                 const f32x2_t xgv = *(const LAS f32x2_t*)xp, xvv = *(const LAS f32x2_t*)(xp + HALF);
;                 unsigned hg = use_x ? pk_bf16(xgv.x, xgv.y) : 0u, hv = use_x ? pk_bf16(xvv.x, xvv.y) : 0u;
;                 if (samp) { const float* sp = sfs + ((size_t)sb * 2 + hsel) * FF2 + c2; const f32x2_t sgv = *(const GAS f32x2_t*)sp, svv = *(const GAS f32x2_t*)(sp + FF); hg = pk_bf16(sgv.x, sgv.y); hv = pk_bf16(svv.x, svv.y); }
.LBB0_1414:
	s_and_b64 vcc, exec, s[10:11]
	s_cbranch_vccnz .LBB0_1416
	s_waitcnt lgkmcnt(0)
	v_cvt_pk_bf16_f32 v150, v230, v231
	v_cvt_pk_bf16_f32 v66, v236, v237
	s_branch .LBB0_1417

; #define GAS __attribute__((address_space(1)))
; #define LAS __attribute__((address_space(3)))
; __device__ __forceinline__ unsigned pk_bf16(float lo, float hi) { f32x2_t v = {lo, hi}; bf16x2_t b = __builtin_convertvector(v, bf16x2_t); return __builtin_bit_cast(unsigned, b); }
;     __device__ __forceinline__ void operator()(EPI_ARGS) const {
;     ...
;             for (int q = 0; q < 4; ++q) {
;                 const int c2 = ch + 2 * q;
;                 const f32x2_t bg = {BG[q >> 1][2 * (q & 1)], BG[q >> 1][2 * (q & 1) + 1]}, bv = {BV[q >> 1][2 * (q & 1)], BV[q >> 1][2 * (q & 1) + 1]};
;                 const LAS float* xp = X + (pred * 2 + hsel) * 256 + cl + 2 * q;
;                 const f32x2_t xgv = *(const LAS f32x2_t*)xp, xvv = *(const LAS f32x2_t*)(xp + HALF);
;                 unsigned hg = use_x ? pk_bf16(xgv.x, xgv.y) : 0u, hv = use_x ? pk_bf16(xvv.x, xvv.y) : 0u;
;                 if (samp) { const float* sp = sfs + ((size_t)sb * 2 + hsel) * FF2 + c2; const f32x2_t sgv = *(const GAS f32x2_t*)sp, svv = *(const GAS f32x2_t*)(sp + FF); hg = pk_bf16(sgv.x, sgv.y); hv = pk_bf16(svv.x, svv.y); }
;                 unsigned rg1 = __builtin_amdgcn_mov_dpp(hg, 0x121, 0xf, 0xf, false), rg2 = __builtin_amdgcn_mov_dpp(hg, 0x122, 0xf, 0xf, false);
;                 unsigned rv1 = __builtin_amdgcn_mov_dpp(hv, 0x121, 0xf, 0xf, false), rv2 = __builtin_amdgcn_mov_dpp(hv, 0x122, 0xf, 0xf, false);
.LBB0_1419:
	s_and_b64 vcc, exec, s[10:11]
	s_cbranch_vccnz .LBB0_1421
	s_waitcnt lgkmcnt(0)
	v_cvt_pk_bf16_f32 v150, v232, v233
	v_cvt_pk_bf16_f32 v66, v238, v239
	s_branch .LBB0_1422

; #define GAS __attribute__((address_space(1)))
; #define LAS __attribute__((address_space(3)))
; __device__ __forceinline__ unsigned pk_bf16(float lo, float hi) { f32x2_t v = {lo, hi}; bf16x2_t b = __builtin_convertvector(v, bf16x2_t); return __builtin_bit_cast(unsigned, b); }
;     __device__ __forceinline__ void operator()(EPI_ARGS) const {
;     ...
;             for (int q = 0; q < 4; ++q) {
;                 const int c2 = ch + 2 * q;
;                 const f32x2_t bg = {BG[q >> 1][2 * (q & 1)], BG[q >> 1][2 * (q & 1) + 1]}, bv = {BV[q >> 1][2 * (q & 1)], BV[q >> 1][2 * (q & 1) + 1]};
;                 const LAS float* xp = X + (pred * 2 + hsel) * 256 + cl + 2 * q;
;                 const f32x2_t xgv = *(const LAS f32x2_t*)xp, xvv = *(const LAS f32x2_t*)(xp + HALF);
;                 unsigned hg = use_x ? pk_bf16(xgv.x, xgv.y) : 0u, hv = use_x ? pk_bf16(xvv.x, xvv.y) : 0u;
;                 if (samp) { const float* sp = sfs + ((size_t)sb * 2 + hsel) * FF2 + c2; const f32x2_t sgv = *(const GAS f32x2_t*)sp, svv = *(const GAS f32x2_t*)(sp + FF); hg = pk_bf16(sgv.x, sgv.y); hv = pk_bf16(svv.x, svv.y); }
;                 unsigned rg1 = __builtin_amdgcn_mov_dpp(hg, 0x121, 0xf, 0xf, false), rg2 = __builtin_amdgcn_mov_dpp(hg, 0x122, 0xf, 0xf, false);
;                 unsigned rv1 = __builtin_amdgcn_mov_dpp(hv, 0x121, 0xf, 0xf, false), rv2 = __builtin_amdgcn_mov_dpp(hv, 0x122, 0xf, 0xf, false);
.LBB0_1424:
	s_and_b64 vcc, exec, s[10:11]
	s_cbranch_vccnz .LBB0_1426
	s_waitcnt lgkmcnt(0)
	v_cvt_pk_bf16_f32 v150, v234, v235
	v_cvt_pk_bf16_f32 v67, v240, v241
	s_branch .LBB0_1427

; #define GAS __attribute__((address_space(1)))
; #define LAS __attribute__((address_space(3)))
; __device__ __forceinline__ unsigned pk_bf16(float lo, float hi) { f32x2_t v = {lo, hi}; bf16x2_t b = __builtin_convertvector(v, bf16x2_t); return __builtin_bit_cast(unsigned, b); }
;     __device__ __forceinline__ void operator()(EPI_ARGS) const {
;     ...
;         for (int ai = 0; ai < 2; ++ai) {
;             const int brow0 = u.row0 + ai * HALF + wr * 64;
;             const int sb = samp ? ((brow0 - MP) >> 6) : 0, pred = (ai * 2 + wr) > 0 ? (ai * 2 + wr - 1) : 0;
;             const bool use_x = !samp && (brow0 & (SEQ - 1)) != 0 && (ai | wr) != 0;
;             const int hsel = fr >= 14 ? fr - 14 : 0;
;             unsigned pk[4][4];
; #pragma unroll
;             for (int q = 0; q < 4; ++q) {
;                 const int c2 = ch + 2 * q;
;                 const f32x2_t bg = {BG[q >> 1][2 * (q & 1)], BG[q >> 1][2 * (q & 1) + 1]}, bv = {BV[q >> 1][2 * (q & 1)], BV[q >> 1][2 * (q & 1) + 1]};
;                 const LAS float* xp = X + (pred * 2 + hsel) * 256 + cl + 2 * q;
;                 const f32x2_t xgv = *(const LAS f32x2_t*)xp, xvv = *(const LAS f32x2_t*)(xp + HALF);
;                 unsigned hg = use_x ? pk_bf16(xgv.x, xgv.y) : 0u, hv = use_x ? pk_bf16(xvv.x, xvv.y) : 0u;
;                 if (samp) { const float* sp = sfs + ((size_t)sb * 2 + hsel) * FF2 + c2; const f32x2_t sgv = *(const GAS f32x2_t*)sp, svv = *(const GAS f32x2_t*)(sp + FF); hg = pk_bf16(sgv.x, sgv.y); hv = pk_bf16(svv.x, svv.y); }
;                 unsigned rg1 = __builtin_amdgcn_mov_dpp(hg, 0x121, 0xf, 0xf, false), rg2 = __builtin_amdgcn_mov_dpp(hg, 0x122, 0xf, 0xf, false);
;                 unsigned rv1 = __builtin_amdgcn_mov_dpp(hv, 0x121, 0xf, 0xf, false), rv2 = __builtin_amdgcn_mov_dpp(hv, 0x122, 0xf, 0xf, false);
.LBB0_1429:
	s_add_i32 s62, s62, 0xffff0080
	s_ashr_i32 s39, s62, 6
	v_lshl_or_b32 v69, s39, 1, v97
	v_mov_b64_e32 v[64:65], s[26:27]
	s_movk_i32 s39, 0x5800
	v_mad_i64_i32 v[64:65], s[48:49], v69, s39, v[64:65]
	s_and_b64 vcc, exec, s[10:11]
	v_lshl_add_u64 v[64:65], v[142:143], 2, v[64:65]
	s_cbranch_vccnz .LBB0_1431
	s_waitcnt lgkmcnt(0)
	v_add_co_u32_e32 v66, vcc, 0x2000, v64
	s_nop 1
	v_addc_co_u32_e32 v67, vcc, 0, v65, vcc
	global_load_dwordx2 v[68:69], v[64:65], off
	global_load_dwordx2 v[230:231], v[64:65], off offset:8
	global_load_dwordx2 v[232:233], v[64:65], off offset:16
	global_load_dwordx2 v[234:235], v[64:65], off offset:24
	global_load_dwordx2 v[236:237], v[66:67], off offset:3080
	global_load_dwordx2 v[238:239], v[66:67], off offset:3088
	global_load_dwordx2 v[240:241], v[66:67], off offset:3096
	s_nop 0
	global_load_dwordx2 v[66:67], v[66:67], off offset:3072
	s_waitcnt vmcnt(7)
	v_cvt_pk_bf16_f32 v68, v68, v69
	s_waitcnt vmcnt(0)
	v_cvt_pk_bf16_f32 v66, v66, v67
	s_branch .LBB0_1432

; #define GAS __attribute__((address_space(1)))
; #define LAS __attribute__((address_space(3)))
; __device__ __forceinline__ unsigned pk_bf16(float lo, float hi) { f32x2_t v = {lo, hi}; bf16x2_t b = __builtin_convertvector(v, bf16x2_t); return __builtin_bit_cast(unsigned, b); }
;     __device__ __forceinline__ void operator()(EPI_ARGS) const {
;     ...
;             for (int q = 0; q < 4; ++q) {
;                 const int c2 = ch + 2 * q;
;                 const f32x2_t bg = {BG[q >> 1][2 * (q & 1)], BG[q >> 1][2 * (q & 1) + 1]}, bv = {BV[q >> 1][2 * (q & 1)], BV[q >> 1][2 * (q & 1) + 1]};
;                 const LAS float* xp = X + (pred * 2 + hsel) * 256 + cl + 2 * q;
;                 const f32x2_t xgv = *(const LAS f32x2_t*)xp, xvv = *(const LAS f32x2_t*)(xp + HALF);
;                 unsigned hg = use_x ? pk_bf16(xgv.x, xgv.y) : 0u, hv = use_x ? pk_bf16(xvv.x, xvv.y) : 0u;
;                 if (samp) { const float* sp = sfs + ((size_t)sb * 2 + hsel) * FF2 + c2; const f32x2_t sgv = *(const GAS f32x2_t*)sp, svv = *(const GAS f32x2_t*)(sp + FF); hg = pk_bf16(sgv.x, sgv.y); hv = pk_bf16(svv.x, svv.y); }
;                 unsigned rg1 = __builtin_amdgcn_mov_dpp(hg, 0x121, 0xf, 0xf, false), rg2 = __builtin_amdgcn_mov_dpp(hg, 0x122, 0xf, 0xf, false);
;                 unsigned rv1 = __builtin_amdgcn_mov_dpp(hv, 0x121, 0xf, 0xf, false), rv2 = __builtin_amdgcn_mov_dpp(hv, 0x122, 0xf, 0xf, false);
.LBB0_1434:
	s_and_b64 vcc, exec, s[10:11]
	s_cbranch_vccnz .LBB0_1436
	s_waitcnt lgkmcnt(0)
	v_cvt_pk_bf16_f32 v69, v230, v231
	v_cvt_pk_bf16_f32 v66, v236, v237
	s_branch .LBB0_1437

; #define GAS __attribute__((address_space(1)))
; #define LAS __attribute__((address_space(3)))
; __device__ __forceinline__ unsigned pk_bf16(float lo, float hi) { f32x2_t v = {lo, hi}; bf16x2_t b = __builtin_convertvector(v, bf16x2_t); return __builtin_bit_cast(unsigned, b); }
;     __device__ __forceinline__ void operator()(EPI_ARGS) const {
;     ...
;             for (int q = 0; q < 4; ++q) {
;                 const int c2 = ch + 2 * q;
;                 const f32x2_t bg = {BG[q >> 1][2 * (q & 1)], BG[q >> 1][2 * (q & 1) + 1]}, bv = {BV[q >> 1][2 * (q & 1)], BV[q >> 1][2 * (q & 1) + 1]};
;                 const LAS float* xp = X + (pred * 2 + hsel) * 256 + cl + 2 * q;
;                 const f32x2_t xgv = *(const LAS f32x2_t*)xp, xvv = *(const LAS f32x2_t*)(xp + HALF);
;                 unsigned hg = use_x ? pk_bf16(xgv.x, xgv.y) : 0u, hv = use_x ? pk_bf16(xvv.x, xvv.y) : 0u;
;                 if (samp) { const float* sp = sfs + ((size_t)sb * 2 + hsel) * FF2 + c2; const f32x2_t sgv = *(const GAS f32x2_t*)sp, svv = *(const GAS f32x2_t*)(sp + FF); hg = pk_bf16(sgv.x, sgv.y); hv = pk_bf16(svv.x, svv.y); }
;                 unsigned rg1 = __builtin_amdgcn_mov_dpp(hg, 0x121, 0xf, 0xf, false), rg2 = __builtin_amdgcn_mov_dpp(hg, 0x122, 0xf, 0xf, false);
;                 unsigned rv1 = __builtin_amdgcn_mov_dpp(hv, 0x121, 0xf, 0xf, false), rv2 = __builtin_amdgcn_mov_dpp(hv, 0x122, 0xf, 0xf, false);
.LBB0_1439:
	s_and_b64 vcc, exec, s[10:11]
	s_cbranch_vccnz .LBB0_1441
	s_waitcnt lgkmcnt(0)
	v_cvt_pk_bf16_f32 v74, v232, v233
	v_cvt_pk_bf16_f32 v66, v238, v239
	s_branch .LBB0_1442

; #define GAS __attribute__((address_space(1)))
; #define LAS __attribute__((address_space(3)))
; __device__ __forceinline__ unsigned pk_bf16(float lo, float hi) { f32x2_t v = {lo, hi}; bf16x2_t b = __builtin_convertvector(v, bf16x2_t); return __builtin_bit_cast(unsigned, b); }
;     __device__ __forceinline__ void operator()(EPI_ARGS) const {
;     ...
;             for (int q = 0; q < 4; ++q) {
;                 const int c2 = ch + 2 * q;
;                 const f32x2_t bg = {BG[q >> 1][2 * (q & 1)], BG[q >> 1][2 * (q & 1) + 1]}, bv = {BV[q >> 1][2 * (q & 1)], BV[q >> 1][2 * (q & 1) + 1]};
;                 const LAS float* xp = X + (pred * 2 + hsel) * 256 + cl + 2 * q;
;                 const f32x2_t xgv = *(const LAS f32x2_t*)xp, xvv = *(const LAS f32x2_t*)(xp + HALF);
;                 unsigned hg = use_x ? pk_bf16(xgv.x, xgv.y) : 0u, hv = use_x ? pk_bf16(xvv.x, xvv.y) : 0u;
;                 if (samp) { const float* sp = sfs + ((size_t)sb * 2 + hsel) * FF2 + c2; const f32x2_t sgv = *(const GAS f32x2_t*)sp, svv = *(const GAS f32x2_t*)(sp + FF); hg = pk_bf16(sgv.x, sgv.y); hv = pk_bf16(svv.x, svv.y); }
;                 unsigned rg1 = __builtin_amdgcn_mov_dpp(hg, 0x121, 0xf, 0xf, false), rg2 = __builtin_amdgcn_mov_dpp(hg, 0x122, 0xf, 0xf, false);
;                 unsigned rv1 = __builtin_amdgcn_mov_dpp(hv, 0x121, 0xf, 0xf, false), rv2 = __builtin_amdgcn_mov_dpp(hv, 0x122, 0xf, 0xf, false);
.LBB0_1444:
	s_and_b64 vcc, exec, s[10:11]
	s_cbranch_vccnz .LBB0_1446
	s_waitcnt lgkmcnt(0)
	v_cvt_pk_bf16_f32 v121, v234, v235
	v_cvt_pk_bf16_f32 v67, v240, v241
	s_branch .LBB0_1447
